# conv_item rewritten: per-token batched tap loads + weights hoisted out of token loop (same f32 math); plus GEMM lgkmcnt waits moved to first consumers
# speedup vs baseline: 1.0595x; 1.0283x over previous
.Ldma_ipb_1:
	s_mov_b64 s[40:41], 0x64000
	s_add_i32 s45, s45, 2
	v_mfma_f32_16x16x32_bf16 v[82:85], v[170:173], v[190:193], v[82:85]
	s_cmp_gt_u32 s45, 28
	s_cbranch_scc1 .Ldma_ipb_2
	s_add_u32 m0, s47, s100
	s_addk_i32 m0, 0x4000
	v_lshl_add_u64 v[244:245], v[208:209], 0, v[206:207]
	global_load_lds_dwordx4 v[244:245], off

.Ldma_ipb_3:
	s_andn2_b64 vcc, exec, s[10:11]
	v_mfma_f32_16x16x32_bf16 v[70:73], v[162:165], v[190:193], v[70:73]
	v_mfma_f32_16x16x32_bf16 v[66:69], v[178:181], v[186:189], v[66:69]
	v_lshl_add_u64 v[208:209], v[208:209], 0, s[40:41]
	v_lshl_add_u64 v[210:211], v[210:211], 0, s[36:37]
	v_lshl_add_u64 v[212:213], v[212:213], 0, s[40:41]
	v_lshl_add_u64 v[214:215], v[214:215], 0, s[36:37]
	v_mfma_f32_16x16x32_bf16 v[62:65], v[170:173], v[186:189], v[62:65]
	v_mfma_f32_16x16x32_bf16 v[46:49], v[166:169], v[186:189], v[46:49]
	v_mfma_f32_16x16x32_bf16 v[42:45], v[162:165], v[186:189], v[42:45]
	v_mfma_f32_16x16x32_bf16 v[34:37], v[178:181], v[182:185], v[34:37]
	v_mfma_f32_16x16x32_bf16 v[30:33], v[170:173], v[182:185], v[30:33]
	v_mfma_f32_16x16x32_bf16 v[26:29], v[166:169], v[182:185], v[26:29]
	v_mfma_f32_16x16x32_bf16 v[22:25], v[162:165], v[182:185], v[22:25]
	v_mfma_f32_16x16x32_bf16 v[18:21], v[178:181], v[174:177], v[18:21]
	v_mfma_f32_16x16x32_bf16 v[98:101], v[170:173], v[174:177], v[98:101]
	v_mfma_f32_16x16x32_bf16 v[90:93], v[166:169], v[174:177], v[90:93]
	v_mfma_f32_16x16x32_bf16 v[74:77], v[162:165], v[174:177], v[74:77]
	s_waitcnt lgkmcnt(0)
	s_cbranch_vccz .LBB0_148

.Ldma_ipa_3:
	v_mfma_f32_16x16x32_bf16 v[46:49], v[8:11], v[54:57], v[46:49]
	v_mfma_f32_16x16x32_bf16 v[42:45], v[12:15], v[54:57], v[42:45]
	ds_read_b128 v[54:57], v202 offset:1024
	v_mfma_f32_16x16x32_bf16 v[34:37], v[0:3], v[50:53], v[34:37]
	v_mfma_f32_16x16x32_bf16 v[30:33], v[4:7], v[50:53], v[30:33]
	v_mfma_f32_16x16x32_bf16 v[26:29], v[8:11], v[50:53], v[26:29]
	v_mfma_f32_16x16x32_bf16 v[22:25], v[12:15], v[50:53], v[22:25]
	ds_read_b128 v[50:53], v202 offset:2048
	ds_read_b128 v[38:41], v202 offset:3072
	s_nop 0
	ds_read_b128 v[190:193], v202 offset:4096
	ds_read_b128 v[186:189], v202 offset:5120
	ds_read_b128 v[182:185], v202 offset:6144
	v_mfma_f32_16x16x32_bf16 v[18:21], v[0:3], v[174:177], v[18:21]
	v_mfma_f32_16x16x32_bf16 v[98:101], v[4:7], v[174:177], v[98:101]
	v_mfma_f32_16x16x32_bf16 v[90:93], v[8:11], v[174:177], v[90:93]
	v_mfma_f32_16x16x32_bf16 v[74:77], v[12:15], v[174:177], v[74:77]
	ds_read_b128 v[174:177], v202 offset:7168
	s_nop 0
	s_waitcnt lgkmcnt(4)
	v_mfma_f32_16x16x32_bf16 v[158:161], v[178:181], v[58:61], v[158:161]
	v_mfma_f32_16x16x32_bf16 v[154:157], v[170:173], v[58:61], v[154:157]
	v_mfma_f32_16x16x32_bf16 v[150:153], v[166:169], v[58:61], v[150:153]
	v_mfma_f32_16x16x32_bf16 v[146:149], v[162:165], v[58:61], v[146:149]
	v_mfma_f32_16x16x32_bf16 v[142:145], v[178:181], v[54:57], v[142:145]
	v_mfma_f32_16x16x32_bf16 v[138:141], v[170:173], v[54:57], v[138:141]
	v_mfma_f32_16x16x32_bf16 v[134:137], v[166:169], v[54:57], v[134:137]
	v_mfma_f32_16x16x32_bf16 v[130:133], v[162:165], v[54:57], v[130:133]
	v_mfma_f32_16x16x32_bf16 v[126:129], v[178:181], v[50:53], v[126:129]
	v_mfma_f32_16x16x32_bf16 v[122:125], v[170:173], v[50:53], v[122:125]
	v_mfma_f32_16x16x32_bf16 v[118:121], v[166:169], v[50:53], v[118:121]
	v_mfma_f32_16x16x32_bf16 v[114:117], v[162:165], v[50:53], v[114:117]
	v_mfma_f32_16x16x32_bf16 v[110:113], v[178:181], v[38:41], v[110:113]
	v_mfma_f32_16x16x32_bf16 v[106:109], v[170:173], v[38:41], v[106:109]
	v_mfma_f32_16x16x32_bf16 v[102:105], v[166:169], v[38:41], v[102:105]
	v_mfma_f32_16x16x32_bf16 v[86:89], v[162:165], v[38:41], v[86:89]
	s_cbranch_vccnz .LBB0_143
	s_min_u32 s42, s44, 2
	s_cmp_lg_u32 s42, 2
	s_mov_b64 s[42:43], -1
	s_cbranch_scc0 .LBB0_141
	s_cmp_lg_u32 s44, 1
	s_cbranch_scc0 .LBB0_138
	s_waitcnt vmcnt(0)
	s_mov_b64 s[42:43], 0

.LBB0_143:
	s_cmp_gt_u32 s45, 26
	s_waitcnt lgkmcnt(0)
	s_barrier

.LBB0_256:
	v_mov_b32_e32 v20, v217
	v_lshlrev_b32_e32 v21, 4, v0
	v_ashrrev_i32_e32 v22, 4, v20
	v_and_b32_e32 v0, -4, v22
	v_lshlrev_b32_e32 v1, 5, v1
	v_add3_u32 v10, v228, v1, v0
	v_add_u32_e32 v23, v0, v21
	v_mad_i64_i32 v[0:1], s[0:1], v10, s33, 0
	v_and_b32_e32 v2, 63, v20
	v_lshlrev_b32_e32 v12, 2, v2
	v_readlane_b32 s0, v252, 19
	v_ashrrev_i32_e32 v11, 31, v10
	v_or_b32_e32 v0, v0, v12
	v_readlane_b32 s1, v252, 20
	v_lshlrev_b64 v[6:7], 11, v[10:11]
	v_lshlrev_b32_e32 v16, 3, v2
	v_lshl_add_u64 v[0:1], s[0:1], 0, v[0:1]
	v_mad_i64_i32 v[10:11], s[0:1], v10, s21, 0
	v_or_b32_e32 v6, v6, v12
	v_or_b32_e32 v10, v10, v12
	v_lshl_add_u64 v[2:3], s[60:61], 0, v[16:17]
	v_lshl_add_u64 v[4:5], s[62:63], 0, v[16:17]
	v_lshl_add_u64 v[6:7], s[6:7], 0, v[6:7]
	v_lshl_add_u64 v[8:9], s[64:65], 0, v[16:17]
	v_lshl_add_u64 v[10:11], s[6:7], 0, v[10:11]
	s_mov_b32 s70, 0
	s_and_b64 vcc, exec, s[10:11]
	s_cbranch_vccz .Lcv_even
	s_mov_b64 s[68:69], 0x1000
	v_lshl_add_u64 v[162:163], v[2:3], 0, s[68:69]
	global_load_dwordx2 v[36:37], v[2:3], off offset:-4096
	global_load_dwordx2 v[38:39], v[2:3], off offset:0
	global_load_dwordx2 v[40:41], v[162:163], off offset:0
	global_load_dwordx2 v[42:43], v[4:5], off offset:0
	global_load_dwordx2 v[44:45], v[2:3], off offset:-3584
	global_load_dwordx2 v[46:47], v[2:3], off offset:512
	global_load_dwordx2 v[48:49], v[162:163], off offset:512
	global_load_dwordx2 v[50:51], v[4:5], off offset:512
	global_load_dwordx2 v[52:53], v[2:3], off offset:-3072
	global_load_dwordx2 v[54:55], v[2:3], off offset:1024
	global_load_dwordx2 v[56:57], v[162:163], off offset:1024
	global_load_dwordx2 v[58:59], v[4:5], off offset:1024
	global_load_dwordx2 v[60:61], v[2:3], off offset:-2560
	global_load_dwordx2 v[62:63], v[2:3], off offset:1536
	global_load_dwordx2 v[64:65], v[162:163], off offset:1536
	global_load_dwordx2 v[66:67], v[4:5], off offset:1536
	global_load_dwordx2 v[68:69], v[2:3], off offset:-2048
	global_load_dwordx2 v[70:71], v[2:3], off offset:2048
	global_load_dwordx2 v[72:73], v[162:163], off offset:2048
	global_load_dwordx2 v[74:75], v[4:5], off offset:2048
	global_load_dwordx2 v[76:77], v[2:3], off offset:-1536
	global_load_dwordx2 v[78:79], v[2:3], off offset:2560
	global_load_dwordx2 v[80:81], v[162:163], off offset:2560
	global_load_dwordx2 v[82:83], v[4:5], off offset:2560
	global_load_dwordx2 v[86:87], v[2:3], off offset:-1024
	global_load_dwordx2 v[88:89], v[2:3], off offset:3072
	global_load_dwordx2 v[90:91], v[162:163], off offset:3072
	global_load_dwordx2 v[92:93], v[4:5], off offset:3072
	global_load_dwordx2 v[94:95], v[2:3], off offset:-512
	global_load_dwordx2 v[96:97], v[2:3], off offset:3584
	global_load_dwordx2 v[98:99], v[162:163], off offset:3584
	global_load_dwordx2 v[100:101], v[4:5], off offset:3584
	s_waitcnt vmcnt(0)
.Lcv_odd_tok:
	v_add_u32_e32 v12, s70, v23
	v_cmp_lt_i32_e32 vcc, s2, v12
	v_mov_b32_e32 v13, 0xff
	v_mov_b32_e32 v14, 0xfff
	v_cndmask_b32_e32 v13, v13, v14, vcc
	v_and_b32_e32 v12, v13, v12
	v_cmp_ne_u32_e64 s[42:43], 0, v12
	v_cmp_ne_u32_e64 s[44:45], v12, v13
	s_mov_b64 s[68:69], 0xa91fc00
	v_lshl_add_u64 v[162:163], v[0:1], 0, s[68:69]
	s_mov_b64 s[68:69], 0xa921000
	v_lshl_add_u64 v[164:165], v[0:1], 0, s[68:69]
	s_mov_b64 s[68:69], 0xa922c00
	v_lshl_add_u64 v[166:167], v[0:1], 0, s[68:69]
	global_load_dword v110, v[162:163], off offset:0
	global_load_dword v111, v[164:165], off offset:1024
	global_load_dword v112, v[166:167], off offset:0
	global_load_dword v113, v[162:163], off offset:256
	global_load_dword v114, v[164:165], off offset:1280
	global_load_dword v115, v[166:167], off offset:256
	global_load_dword v116, v[162:163], off offset:512
	global_load_dword v117, v[164:165], off offset:1536
	global_load_dword v118, v[166:167], off offset:512
	global_load_dword v119, v[162:163], off offset:768
	global_load_dword v120, v[164:165], off offset:1792
	global_load_dword v121, v[166:167], off offset:768
	global_load_dword v122, v[162:163], off offset:1024
	global_load_dword v123, v[164:165], off offset:2048
	global_load_dword v124, v[166:167], off offset:1024
	global_load_dword v125, v[162:163], off offset:1280
	global_load_dword v126, v[164:165], off offset:2304
	global_load_dword v127, v[166:167], off offset:1280
	global_load_dword v128, v[162:163], off offset:1536
	global_load_dword v129, v[164:165], off offset:2560
	global_load_dword v130, v[166:167], off offset:1536
	global_load_dword v131, v[162:163], off offset:1792
	global_load_dword v132, v[164:165], off offset:2816
	global_load_dword v133, v[166:167], off offset:1792
	s_waitcnt vmcnt(21)
	v_cndmask_b32_e64 v110, 0, v110, s[42:43]
	v_cndmask_b32_e64 v112, 0, v112, s[44:45]
	v_lshlrev_b32_e32 v154, 16, v111
	v_and_b32_e32 v155, 0xffff0000, v111
	v_lshlrev_b32_e32 v156, 16, v110
	v_and_b32_e32 v157, 0xffff0000, v110
	v_lshlrev_b32_e32 v158, 16, v112
	v_and_b32_e32 v159, 0xffff0000, v112
	v_pk_mul_f32 v[150:151], v[38:39], v[154:155]
	s_nop 0
	v_pk_fma_f32 v[150:151], v[36:37], v[156:157], v[150:151]
	v_pk_fma_f32 v[150:151], v[40:41], v[158:159], v[150:151]
	v_pk_add_f32 v[150:151], v[150:151], v[42:43]
	s_nop 0
	v_mul_f32_e32 v146, 0xbfb8aa3b, v150
	v_exp_f32_e32 v152, v146
	v_mul_f32_e32 v146, 0xbfb8aa3b, v151
	v_exp_f32_e32 v153, v146
	s_nop 0
	v_pk_add_f32 v[152:153], v[152:153], 1.0 op_sel_hi:[1,0]
	s_nop 0
	v_div_scale_f32 v146, s[68:69], v153, v153, v151
	v_rcp_f32_e32 v147, v146
	s_nop 0
	v_fma_f32 v148, -v146, v147, 1.0
	v_fmac_f32_e32 v147, v148, v147
	v_div_scale_f32 v148, vcc, v151, v153, v151
	v_mul_f32_e32 v160, v148, v147
	v_fma_f32 v161, -v146, v160, v148
	v_fmac_f32_e32 v160, v161, v147
	v_fma_f32 v146, -v146, v160, v148
	v_div_fmas_f32 v146, v146, v147, v160
	v_div_fixup_f32 v151, v146, v153, v151
	v_div_scale_f32 v146, s[68:69], v152, v152, v150
	v_rcp_f32_e32 v147, v146
	s_nop 0
	v_fma_f32 v148, -v146, v147, 1.0
	v_fmac_f32_e32 v147, v148, v147
	v_div_scale_f32 v148, vcc, v150, v152, v150
	v_mul_f32_e32 v160, v148, v147
	v_fma_f32 v161, -v146, v160, v148
	v_fmac_f32_e32 v160, v161, v147
	v_fma_f32 v146, -v146, v160, v148
	v_div_fmas_f32 v146, v146, v147, v160
	v_div_fixup_f32 v150, v146, v152, v150
	v_cvt_pk_bf16_f32 v146, v150, v151
	global_store_dword v[6:7], v146, off offset:0
	s_waitcnt vmcnt(19)
	v_cndmask_b32_e64 v113, 0, v113, s[42:43]
	v_cndmask_b32_e64 v115, 0, v115, s[44:45]
	v_lshlrev_b32_e32 v154, 16, v114
	v_and_b32_e32 v155, 0xffff0000, v114
	v_lshlrev_b32_e32 v156, 16, v113
	v_and_b32_e32 v157, 0xffff0000, v113
	v_lshlrev_b32_e32 v158, 16, v115
	v_and_b32_e32 v159, 0xffff0000, v115
	v_pk_mul_f32 v[150:151], v[46:47], v[154:155]
	s_nop 0
	v_pk_fma_f32 v[150:151], v[44:45], v[156:157], v[150:151]
	v_pk_fma_f32 v[150:151], v[48:49], v[158:159], v[150:151]
	v_pk_add_f32 v[150:151], v[150:151], v[50:51]
	s_nop 0
	v_mul_f32_e32 v146, 0xbfb8aa3b, v150
	v_exp_f32_e32 v152, v146
	v_mul_f32_e32 v146, 0xbfb8aa3b, v151
	v_exp_f32_e32 v153, v146
	s_nop 0
	v_pk_add_f32 v[152:153], v[152:153], 1.0 op_sel_hi:[1,0]
	s_nop 0
	v_div_scale_f32 v146, s[68:69], v153, v153, v151
	v_rcp_f32_e32 v147, v146
	s_nop 0
	v_fma_f32 v148, -v146, v147, 1.0
	v_fmac_f32_e32 v147, v148, v147
	v_div_scale_f32 v148, vcc, v151, v153, v151
	v_mul_f32_e32 v160, v148, v147
	v_fma_f32 v161, -v146, v160, v148
	v_fmac_f32_e32 v160, v161, v147
	v_fma_f32 v146, -v146, v160, v148
	v_div_fmas_f32 v146, v146, v147, v160
	v_div_fixup_f32 v151, v146, v153, v151
	v_div_scale_f32 v146, s[68:69], v152, v152, v150
	v_rcp_f32_e32 v147, v146
	s_nop 0
	v_fma_f32 v148, -v146, v147, 1.0
	v_fmac_f32_e32 v147, v148, v147
	v_div_scale_f32 v148, vcc, v150, v152, v150
	v_mul_f32_e32 v160, v148, v147
	v_fma_f32 v161, -v146, v160, v148
	v_fmac_f32_e32 v160, v161, v147
	v_fma_f32 v146, -v146, v160, v148
	v_div_fmas_f32 v146, v146, v147, v160
	v_div_fixup_f32 v150, v146, v152, v150
	v_cvt_pk_bf16_f32 v146, v150, v151
	global_store_dword v[6:7], v146, off offset:256
	s_waitcnt vmcnt(17)
	v_cndmask_b32_e64 v116, 0, v116, s[42:43]
	v_cndmask_b32_e64 v118, 0, v118, s[44:45]
	v_lshlrev_b32_e32 v154, 16, v117
	v_and_b32_e32 v155, 0xffff0000, v117
	v_lshlrev_b32_e32 v156, 16, v116
	v_and_b32_e32 v157, 0xffff0000, v116
	v_lshlrev_b32_e32 v158, 16, v118
	v_and_b32_e32 v159, 0xffff0000, v118
	v_pk_mul_f32 v[150:151], v[54:55], v[154:155]
	s_nop 0
	v_pk_fma_f32 v[150:151], v[52:53], v[156:157], v[150:151]
	v_pk_fma_f32 v[150:151], v[56:57], v[158:159], v[150:151]
	v_pk_add_f32 v[150:151], v[150:151], v[58:59]
	s_nop 0
	v_mul_f32_e32 v146, 0xbfb8aa3b, v150
	v_exp_f32_e32 v152, v146
	v_mul_f32_e32 v146, 0xbfb8aa3b, v151
	v_exp_f32_e32 v153, v146
	s_nop 0
	v_pk_add_f32 v[152:153], v[152:153], 1.0 op_sel_hi:[1,0]
	s_nop 0
	v_div_scale_f32 v146, s[68:69], v153, v153, v151
	v_rcp_f32_e32 v147, v146
	s_nop 0
	v_fma_f32 v148, -v146, v147, 1.0
	v_fmac_f32_e32 v147, v148, v147
	v_div_scale_f32 v148, vcc, v151, v153, v151
	v_mul_f32_e32 v160, v148, v147
	v_fma_f32 v161, -v146, v160, v148
	v_fmac_f32_e32 v160, v161, v147
	v_fma_f32 v146, -v146, v160, v148
	v_div_fmas_f32 v146, v146, v147, v160
	v_div_fixup_f32 v151, v146, v153, v151
	v_div_scale_f32 v146, s[68:69], v152, v152, v150
	v_rcp_f32_e32 v147, v146
	s_nop 0
	v_fma_f32 v148, -v146, v147, 1.0
	v_fmac_f32_e32 v147, v148, v147
	v_div_scale_f32 v148, vcc, v150, v152, v150
	v_mul_f32_e32 v160, v148, v147
	v_fma_f32 v161, -v146, v160, v148
	v_fmac_f32_e32 v160, v161, v147
	v_fma_f32 v146, -v146, v160, v148
	v_div_fmas_f32 v146, v146, v147, v160
	v_div_fixup_f32 v150, v146, v152, v150
	v_cvt_pk_bf16_f32 v146, v150, v151
	global_store_dword v[6:7], v146, off offset:512
	s_waitcnt vmcnt(15)
	v_cndmask_b32_e64 v119, 0, v119, s[42:43]
	v_cndmask_b32_e64 v121, 0, v121, s[44:45]
	v_lshlrev_b32_e32 v154, 16, v120
	v_and_b32_e32 v155, 0xffff0000, v120
	v_lshlrev_b32_e32 v156, 16, v119
	v_and_b32_e32 v157, 0xffff0000, v119
	v_lshlrev_b32_e32 v158, 16, v121
	v_and_b32_e32 v159, 0xffff0000, v121
	v_pk_mul_f32 v[150:151], v[62:63], v[154:155]
	s_nop 0
	v_pk_fma_f32 v[150:151], v[60:61], v[156:157], v[150:151]
	v_pk_fma_f32 v[150:151], v[64:65], v[158:159], v[150:151]
	v_pk_add_f32 v[150:151], v[150:151], v[66:67]
	s_nop 0
	v_mul_f32_e32 v146, 0xbfb8aa3b, v150
	v_exp_f32_e32 v152, v146
	v_mul_f32_e32 v146, 0xbfb8aa3b, v151
	v_exp_f32_e32 v153, v146
	s_nop 0
	v_pk_add_f32 v[152:153], v[152:153], 1.0 op_sel_hi:[1,0]
	s_nop 0
	v_div_scale_f32 v146, s[68:69], v153, v153, v151
	v_rcp_f32_e32 v147, v146
	s_nop 0
	v_fma_f32 v148, -v146, v147, 1.0
	v_fmac_f32_e32 v147, v148, v147
	v_div_scale_f32 v148, vcc, v151, v153, v151
	v_mul_f32_e32 v160, v148, v147
	v_fma_f32 v161, -v146, v160, v148
	v_fmac_f32_e32 v160, v161, v147
	v_fma_f32 v146, -v146, v160, v148
	v_div_fmas_f32 v146, v146, v147, v160
	v_div_fixup_f32 v151, v146, v153, v151
	v_div_scale_f32 v146, s[68:69], v152, v152, v150
	v_rcp_f32_e32 v147, v146
	s_nop 0
	v_fma_f32 v148, -v146, v147, 1.0
	v_fmac_f32_e32 v147, v148, v147
	v_div_scale_f32 v148, vcc, v150, v152, v150
	v_mul_f32_e32 v160, v148, v147
	v_fma_f32 v161, -v146, v160, v148
	v_fmac_f32_e32 v160, v161, v147
	v_fma_f32 v146, -v146, v160, v148
	v_div_fmas_f32 v146, v146, v147, v160
	v_div_fixup_f32 v150, v146, v152, v150
	v_cvt_pk_bf16_f32 v146, v150, v151
	global_store_dword v[6:7], v146, off offset:768
	s_waitcnt vmcnt(13)
	v_cndmask_b32_e64 v122, 0, v122, s[42:43]
	v_cndmask_b32_e64 v124, 0, v124, s[44:45]
	v_lshlrev_b32_e32 v154, 16, v123
	v_and_b32_e32 v155, 0xffff0000, v123
	v_lshlrev_b32_e32 v156, 16, v122
	v_and_b32_e32 v157, 0xffff0000, v122
	v_lshlrev_b32_e32 v158, 16, v124
	v_and_b32_e32 v159, 0xffff0000, v124
	v_pk_mul_f32 v[150:151], v[70:71], v[154:155]
	s_nop 0
	v_pk_fma_f32 v[150:151], v[68:69], v[156:157], v[150:151]
	v_pk_fma_f32 v[150:151], v[72:73], v[158:159], v[150:151]
	v_pk_add_f32 v[150:151], v[150:151], v[74:75]
	s_nop 0
	v_mul_f32_e32 v146, 0xbfb8aa3b, v150
	v_exp_f32_e32 v152, v146
	v_mul_f32_e32 v146, 0xbfb8aa3b, v151
	v_exp_f32_e32 v153, v146
	s_nop 0
	v_pk_add_f32 v[152:153], v[152:153], 1.0 op_sel_hi:[1,0]
	s_nop 0
	v_div_scale_f32 v146, s[68:69], v153, v153, v151
	v_rcp_f32_e32 v147, v146
	s_nop 0
	v_fma_f32 v148, -v146, v147, 1.0
	v_fmac_f32_e32 v147, v148, v147
	v_div_scale_f32 v148, vcc, v151, v153, v151
	v_mul_f32_e32 v160, v148, v147
	v_fma_f32 v161, -v146, v160, v148
	v_fmac_f32_e32 v160, v161, v147
	v_fma_f32 v146, -v146, v160, v148
	v_div_fmas_f32 v146, v146, v147, v160
	v_div_fixup_f32 v151, v146, v153, v151
	v_div_scale_f32 v146, s[68:69], v152, v152, v150
	v_rcp_f32_e32 v147, v146
	s_nop 0
	v_fma_f32 v148, -v146, v147, 1.0
	v_fmac_f32_e32 v147, v148, v147
	v_div_scale_f32 v148, vcc, v150, v152, v150
	v_mul_f32_e32 v160, v148, v147
	v_fma_f32 v161, -v146, v160, v148
	v_fmac_f32_e32 v160, v161, v147
	v_fma_f32 v146, -v146, v160, v148
	v_div_fmas_f32 v146, v146, v147, v160
	v_div_fixup_f32 v150, v146, v152, v150
	v_cvt_pk_bf16_f32 v146, v150, v151
	global_store_dword v[6:7], v146, off offset:1024
	s_waitcnt vmcnt(11)
	v_cndmask_b32_e64 v125, 0, v125, s[42:43]
	v_cndmask_b32_e64 v127, 0, v127, s[44:45]
	v_lshlrev_b32_e32 v154, 16, v126
	v_and_b32_e32 v155, 0xffff0000, v126
	v_lshlrev_b32_e32 v156, 16, v125
	v_and_b32_e32 v157, 0xffff0000, v125
	v_lshlrev_b32_e32 v158, 16, v127
	v_and_b32_e32 v159, 0xffff0000, v127
	v_pk_mul_f32 v[150:151], v[78:79], v[154:155]
	s_nop 0
	v_pk_fma_f32 v[150:151], v[76:77], v[156:157], v[150:151]
	v_pk_fma_f32 v[150:151], v[80:81], v[158:159], v[150:151]
	v_pk_add_f32 v[150:151], v[150:151], v[82:83]
	s_nop 0
	v_mul_f32_e32 v146, 0xbfb8aa3b, v150
	v_exp_f32_e32 v152, v146
	v_mul_f32_e32 v146, 0xbfb8aa3b, v151
	v_exp_f32_e32 v153, v146
	s_nop 0
	v_pk_add_f32 v[152:153], v[152:153], 1.0 op_sel_hi:[1,0]
	s_nop 0
	v_div_scale_f32 v146, s[68:69], v153, v153, v151
	v_rcp_f32_e32 v147, v146
	s_nop 0
	v_fma_f32 v148, -v146, v147, 1.0
	v_fmac_f32_e32 v147, v148, v147
	v_div_scale_f32 v148, vcc, v151, v153, v151
	v_mul_f32_e32 v160, v148, v147
	v_fma_f32 v161, -v146, v160, v148
	v_fmac_f32_e32 v160, v161, v147
	v_fma_f32 v146, -v146, v160, v148
	v_div_fmas_f32 v146, v146, v147, v160
	v_div_fixup_f32 v151, v146, v153, v151
	v_div_scale_f32 v146, s[68:69], v152, v152, v150
	v_rcp_f32_e32 v147, v146
	s_nop 0
	v_fma_f32 v148, -v146, v147, 1.0
	v_fmac_f32_e32 v147, v148, v147
	v_div_scale_f32 v148, vcc, v150, v152, v150
	v_mul_f32_e32 v160, v148, v147
	v_fma_f32 v161, -v146, v160, v148
	v_fmac_f32_e32 v160, v161, v147
	v_fma_f32 v146, -v146, v160, v148
	v_div_fmas_f32 v146, v146, v147, v160
	v_div_fixup_f32 v150, v146, v152, v150
	v_cvt_pk_bf16_f32 v146, v150, v151
	global_store_dword v[6:7], v146, off offset:1280
	s_waitcnt vmcnt(9)
	v_cndmask_b32_e64 v128, 0, v128, s[42:43]
	v_cndmask_b32_e64 v130, 0, v130, s[44:45]
	v_lshlrev_b32_e32 v154, 16, v129
	v_and_b32_e32 v155, 0xffff0000, v129
	v_lshlrev_b32_e32 v156, 16, v128
	v_and_b32_e32 v157, 0xffff0000, v128
	v_lshlrev_b32_e32 v158, 16, v130
	v_and_b32_e32 v159, 0xffff0000, v130
	v_pk_mul_f32 v[150:151], v[88:89], v[154:155]
	s_nop 0
	v_pk_fma_f32 v[150:151], v[86:87], v[156:157], v[150:151]
	v_pk_fma_f32 v[150:151], v[90:91], v[158:159], v[150:151]
	v_pk_add_f32 v[150:151], v[150:151], v[92:93]
	s_nop 0
	v_mul_f32_e32 v146, 0xbfb8aa3b, v150
	v_exp_f32_e32 v152, v146
	v_mul_f32_e32 v146, 0xbfb8aa3b, v151
	v_exp_f32_e32 v153, v146
	s_nop 0
	v_pk_add_f32 v[152:153], v[152:153], 1.0 op_sel_hi:[1,0]
	s_nop 0
	v_div_scale_f32 v146, s[68:69], v153, v153, v151
	v_rcp_f32_e32 v147, v146
	s_nop 0
	v_fma_f32 v148, -v146, v147, 1.0
	v_fmac_f32_e32 v147, v148, v147
	v_div_scale_f32 v148, vcc, v151, v153, v151
	v_mul_f32_e32 v160, v148, v147
	v_fma_f32 v161, -v146, v160, v148
	v_fmac_f32_e32 v160, v161, v147
	v_fma_f32 v146, -v146, v160, v148
	v_div_fmas_f32 v146, v146, v147, v160
	v_div_fixup_f32 v151, v146, v153, v151
	v_div_scale_f32 v146, s[68:69], v152, v152, v150
	v_rcp_f32_e32 v147, v146
	s_nop 0
	v_fma_f32 v148, -v146, v147, 1.0
	v_fmac_f32_e32 v147, v148, v147
	v_div_scale_f32 v148, vcc, v150, v152, v150
	v_mul_f32_e32 v160, v148, v147
	v_fma_f32 v161, -v146, v160, v148
	v_fmac_f32_e32 v160, v161, v147
	v_fma_f32 v146, -v146, v160, v148
	v_div_fmas_f32 v146, v146, v147, v160
	v_div_fixup_f32 v150, v146, v152, v150
	v_cvt_pk_bf16_f32 v146, v150, v151
	global_store_dword v[6:7], v146, off offset:1536
	s_waitcnt vmcnt(7)
	v_cndmask_b32_e64 v131, 0, v131, s[42:43]
	v_cndmask_b32_e64 v133, 0, v133, s[44:45]
	v_lshlrev_b32_e32 v154, 16, v132
	v_and_b32_e32 v155, 0xffff0000, v132
	v_lshlrev_b32_e32 v156, 16, v131
	v_and_b32_e32 v157, 0xffff0000, v131
	v_lshlrev_b32_e32 v158, 16, v133
	v_and_b32_e32 v159, 0xffff0000, v133
	v_pk_mul_f32 v[150:151], v[96:97], v[154:155]
	s_nop 0
	v_pk_fma_f32 v[150:151], v[94:95], v[156:157], v[150:151]
	v_pk_fma_f32 v[150:151], v[98:99], v[158:159], v[150:151]
	v_pk_add_f32 v[150:151], v[150:151], v[100:101]
	s_nop 0
	v_mul_f32_e32 v146, 0xbfb8aa3b, v150
	v_exp_f32_e32 v152, v146
	v_mul_f32_e32 v146, 0xbfb8aa3b, v151
	v_exp_f32_e32 v153, v146
	s_nop 0
	v_pk_add_f32 v[152:153], v[152:153], 1.0 op_sel_hi:[1,0]
	s_nop 0
	v_div_scale_f32 v146, s[68:69], v153, v153, v151
	v_rcp_f32_e32 v147, v146
	s_nop 0
	v_fma_f32 v148, -v146, v147, 1.0
	v_fmac_f32_e32 v147, v148, v147
	v_div_scale_f32 v148, vcc, v151, v153, v151
	v_mul_f32_e32 v160, v148, v147
	v_fma_f32 v161, -v146, v160, v148
	v_fmac_f32_e32 v160, v161, v147
	v_fma_f32 v146, -v146, v160, v148
	v_div_fmas_f32 v146, v146, v147, v160
	v_div_fixup_f32 v151, v146, v153, v151
	v_div_scale_f32 v146, s[68:69], v152, v152, v150
	v_rcp_f32_e32 v147, v146
	s_nop 0
	v_fma_f32 v148, -v146, v147, 1.0
	v_fmac_f32_e32 v147, v148, v147
	v_div_scale_f32 v148, vcc, v150, v152, v150
	v_mul_f32_e32 v160, v148, v147
	v_fma_f32 v161, -v146, v160, v148
	v_fmac_f32_e32 v160, v161, v147
	v_fma_f32 v146, -v146, v160, v148
	v_div_fmas_f32 v146, v146, v147, v160
	v_div_fixup_f32 v150, v146, v152, v150
	v_cvt_pk_bf16_f32 v146, v150, v151
	global_store_dword v[6:7], v146, off offset:1792
	s_mov_b64 s[68:69], 0x1800
	v_lshl_add_u64 v[0:1], v[0:1], 0, s[68:69]
	s_mov_b64 s[68:69], 0x800
	v_lshl_add_u64 v[6:7], v[6:7], 0, s[68:69]
	s_add_i32 s70, s70, 1
	s_cmp_lg_u32 s70, 4
	s_cbranch_scc1 .Lcv_odd_tok
	s_branch .LBB0_275
.Lcv_even:
	s_mov_b64 s[68:69], 0x1000
	v_lshl_add_u64 v[162:163], v[8:9], 0, s[68:69]
	s_mov_b64 s[68:69], 0x1800
	v_lshl_add_u64 v[164:165], v[8:9], 0, s[68:69]
	s_mov_b64 s[68:69], 0x2800
	v_lshl_add_u64 v[166:167], v[8:9], 0, s[68:69]
	s_mov_b64 s[68:69], 0x3000
	v_lshl_add_u64 v[168:169], v[8:9], 0, s[68:69]
	s_mov_b64 s[68:69], 0x4000
	v_lshl_add_u64 v[170:171], v[8:9], 0, s[68:69]
	global_load_dwordx2 v[36:37], v[8:9], off offset:0
	global_load_dwordx2 v[38:39], v[164:165], off offset:0
	global_load_dwordx2 v[40:41], v[168:169], off offset:0
	global_load_dwordx2 v[42:43], v[8:9], off offset:512
	global_load_dwordx2 v[44:45], v[164:165], off offset:512
	global_load_dwordx2 v[46:47], v[168:169], off offset:512
	global_load_dwordx2 v[48:49], v[8:9], off offset:1024
	global_load_dwordx2 v[50:51], v[164:165], off offset:1024
	global_load_dwordx2 v[52:53], v[168:169], off offset:1024
	global_load_dwordx2 v[54:55], v[8:9], off offset:1536
	global_load_dwordx2 v[56:57], v[164:165], off offset:1536
	global_load_dwordx2 v[58:59], v[168:169], off offset:1536
	global_load_dwordx2 v[60:61], v[8:9], off offset:2048
	global_load_dwordx2 v[62:63], v[164:165], off offset:2048
	global_load_dwordx2 v[64:65], v[168:169], off offset:2048
	global_load_dwordx2 v[66:67], v[8:9], off offset:2560
	global_load_dwordx2 v[68:69], v[164:165], off offset:2560
	global_load_dwordx2 v[70:71], v[168:169], off offset:2560
	global_load_dwordx2 v[72:73], v[8:9], off offset:3072
	global_load_dwordx2 v[74:75], v[164:165], off offset:3072
	global_load_dwordx2 v[76:77], v[168:169], off offset:3072
	global_load_dwordx2 v[78:79], v[8:9], off offset:3584
	global_load_dwordx2 v[80:81], v[164:165], off offset:3584
	global_load_dwordx2 v[82:83], v[168:169], off offset:3584
	global_load_dwordx2 v[86:87], v[162:163], off offset:0
	global_load_dwordx2 v[88:89], v[166:167], off offset:0
	global_load_dwordx2 v[90:91], v[170:171], off offset:0
	global_load_dwordx2 v[92:93], v[162:163], off offset:512
	global_load_dwordx2 v[94:95], v[166:167], off offset:512
	global_load_dwordx2 v[96:97], v[170:171], off offset:512
	global_load_dwordx2 v[98:99], v[162:163], off offset:1024
	global_load_dwordx2 v[100:101], v[166:167], off offset:1024
	global_load_dwordx2 v[102:103], v[170:171], off offset:1024
	global_load_dwordx2 v[104:105], v[162:163], off offset:1536
	global_load_dwordx2 v[106:107], v[166:167], off offset:1536
	global_load_dwordx2 v[108:109], v[170:171], off offset:1536
	s_waitcnt vmcnt(0)
.Lcv_even_tok:
	v_add_u32_e32 v12, s70, v23
	v_cmp_lt_i32_e32 vcc, s2, v12
	v_mov_b32_e32 v13, 0xff
	v_mov_b32_e32 v14, 0xfff
	v_cndmask_b32_e32 v13, v13, v14, vcc
	v_and_b32_e32 v12, v13, v12
	v_cmp_ne_u32_e64 s[42:43], 0, v12
	v_cmp_ne_u32_e64 s[44:45], v12, v13
	s_mov_b64 s[68:69], 0xa91f800
	v_lshl_add_u64 v[162:163], v[0:1], 0, s[68:69]
	s_mov_b64 s[68:69], 0xa921000
	v_lshl_add_u64 v[164:165], v[0:1], 0, s[68:69]
	s_mov_b64 s[68:69], 0xa922800
	v_lshl_add_u64 v[166:167], v[0:1], 0, s[68:69]
	global_load_dword v110, v[162:163], off offset:0
	global_load_dword v111, v[164:165], off offset:0
	global_load_dword v112, v[166:167], off offset:0
	global_load_dword v113, v[162:163], off offset:256
	global_load_dword v114, v[164:165], off offset:256
	global_load_dword v115, v[166:167], off offset:256
	global_load_dword v116, v[162:163], off offset:512
	global_load_dword v117, v[164:165], off offset:512
	global_load_dword v118, v[166:167], off offset:512
	global_load_dword v119, v[162:163], off offset:768
	global_load_dword v120, v[164:165], off offset:768
	global_load_dword v121, v[166:167], off offset:768
	global_load_dword v122, v[162:163], off offset:1024
	global_load_dword v123, v[164:165], off offset:1024
	global_load_dword v124, v[166:167], off offset:1024
	global_load_dword v125, v[162:163], off offset:1280
	global_load_dword v126, v[164:165], off offset:1280
	global_load_dword v127, v[166:167], off offset:1280
	global_load_dword v128, v[162:163], off offset:1536
	global_load_dword v129, v[164:165], off offset:1536
	global_load_dword v130, v[166:167], off offset:1536
	global_load_dword v131, v[162:163], off offset:1792
	global_load_dword v132, v[164:165], off offset:1792
	global_load_dword v133, v[166:167], off offset:1792
	global_load_dword v134, v[162:163], off offset:2048
	global_load_dword v135, v[164:165], off offset:2048
	global_load_dword v136, v[166:167], off offset:2048
	global_load_dword v137, v[162:163], off offset:2304
	global_load_dword v138, v[164:165], off offset:2304
	global_load_dword v139, v[166:167], off offset:2304
	global_load_dword v140, v[162:163], off offset:2560
	global_load_dword v141, v[164:165], off offset:2560
	global_load_dword v142, v[166:167], off offset:2560
	global_load_dword v143, v[162:163], off offset:2816
	global_load_dword v144, v[164:165], off offset:2816
	global_load_dword v145, v[166:167], off offset:2816
	s_waitcnt vmcnt(33)
	v_cndmask_b32_e64 v110, 0, v110, s[42:43]
	v_cndmask_b32_e64 v112, 0, v112, s[44:45]
	v_lshlrev_b32_e32 v154, 16, v111
	v_and_b32_e32 v155, 0xffff0000, v111
	v_lshlrev_b32_e32 v156, 16, v110
	v_and_b32_e32 v157, 0xffff0000, v110
	v_lshlrev_b32_e32 v158, 16, v112
	v_and_b32_e32 v159, 0xffff0000, v112
	v_pk_mul_f32 v[150:151], v[38:39], v[154:155]
	s_nop 0
	v_pk_fma_f32 v[150:151], v[36:37], v[156:157], v[150:151]
	v_pk_fma_f32 v[150:151], v[40:41], v[158:159], v[150:151]
	s_nop 0
	v_mul_f32_e32 v146, 0xbfb8aa3b, v150
	v_exp_f32_e32 v152, v146
	v_mul_f32_e32 v146, 0xbfb8aa3b, v151
	v_exp_f32_e32 v153, v146
	s_nop 0
	v_pk_add_f32 v[152:153], v[152:153], 1.0 op_sel_hi:[1,0]
	s_nop 0
	v_div_scale_f32 v146, s[68:69], v153, v153, v151
	v_rcp_f32_e32 v147, v146
	s_nop 0
	v_fma_f32 v148, -v146, v147, 1.0
	v_fmac_f32_e32 v147, v148, v147
	v_div_scale_f32 v148, vcc, v151, v153, v151
	v_mul_f32_e32 v160, v148, v147
	v_fma_f32 v161, -v146, v160, v148
	v_fmac_f32_e32 v160, v161, v147
	v_fma_f32 v146, -v146, v160, v148
	v_div_fmas_f32 v146, v146, v147, v160
	v_div_fixup_f32 v151, v146, v153, v151
	v_div_scale_f32 v146, s[68:69], v152, v152, v150
	v_rcp_f32_e32 v147, v146
	s_nop 0
	v_fma_f32 v148, -v146, v147, 1.0
	v_fmac_f32_e32 v147, v148, v147
	v_div_scale_f32 v148, vcc, v150, v152, v150
	v_mul_f32_e32 v160, v148, v147
	v_fma_f32 v161, -v146, v160, v148
	v_fmac_f32_e32 v160, v161, v147
	v_fma_f32 v146, -v146, v160, v148
	v_div_fmas_f32 v146, v146, v147, v160
	v_div_fixup_f32 v150, v146, v152, v150
	v_pk_mul_f32 v[154:155], v[150:151], v[150:151]
	v_add_f32_e32 v148, v154, v155
	s_nop 1
	v_add_f32_dpp v148, v148, v148 quad_perm:[1,0,3,2] row_mask:0xf bank_mask:0xf
	s_nop 1
	v_add_f32_dpp v148, v148, v148 quad_perm:[2,3,0,1] row_mask:0xf bank_mask:0xf
	s_nop 1
	v_add_f32_dpp v148, v148, v148 row_half_mirror row_mask:0xf bank_mask:0xf
	s_nop 1
	v_add_f32_dpp v148, v148, v148 row_mirror row_mask:0xf bank_mask:0xf
	v_mov_b32_e32 v154, v148
	s_nop 1
	v_permlane16_swap_b32_e32 v148, v154
	v_add_f32_e32 v148, v148, v154
	v_mov_b32_e32 v154, v148
	s_nop 1
	v_permlane32_swap_b32_e32 v148, v154
	v_add_f32_e32 v148, v148, v154
	v_add_f32_e32 v148, 0x358637bd, v148
	v_cmp_gt_f32_e32 vcc, s3, v148
	v_mul_f32_e32 v154, 0x4b800000, v148
	s_nop 0
	v_cndmask_b32_e32 v148, v148, v154, vcc
	v_rsq_f32_e32 v148, v148
	s_nop 0
	v_mul_f32_e32 v154, 0x45800000, v148
	v_cndmask_b32_e32 v148, v148, v154, vcc
	v_mul_f32_e32 v148, 0x3db504f3, v148
	v_pk_mul_f32 v[150:151], v[150:151], v[148:149] op_sel_hi:[1,0]
	s_nop 0
	v_cvt_pk_bf16_f32 v146, v150, v151
	global_store_dword v[10:11], v146, off offset:0
	s_waitcnt vmcnt(31)
	v_cndmask_b32_e64 v113, 0, v113, s[42:43]
	v_cndmask_b32_e64 v115, 0, v115, s[44:45]
	v_lshlrev_b32_e32 v154, 16, v114
	v_and_b32_e32 v155, 0xffff0000, v114
	v_lshlrev_b32_e32 v156, 16, v113
	v_and_b32_e32 v157, 0xffff0000, v113
	v_lshlrev_b32_e32 v158, 16, v115
	v_and_b32_e32 v159, 0xffff0000, v115
	v_pk_mul_f32 v[150:151], v[44:45], v[154:155]
	s_nop 0
	v_pk_fma_f32 v[150:151], v[42:43], v[156:157], v[150:151]
	v_pk_fma_f32 v[150:151], v[46:47], v[158:159], v[150:151]
	s_nop 0
	v_mul_f32_e32 v146, 0xbfb8aa3b, v150
	v_exp_f32_e32 v152, v146
	v_mul_f32_e32 v146, 0xbfb8aa3b, v151
	v_exp_f32_e32 v153, v146
	s_nop 0
	v_pk_add_f32 v[152:153], v[152:153], 1.0 op_sel_hi:[1,0]
	s_nop 0
	v_div_scale_f32 v146, s[68:69], v153, v153, v151
	v_rcp_f32_e32 v147, v146
	s_nop 0
	v_fma_f32 v148, -v146, v147, 1.0
	v_fmac_f32_e32 v147, v148, v147
	v_div_scale_f32 v148, vcc, v151, v153, v151
	v_mul_f32_e32 v160, v148, v147
	v_fma_f32 v161, -v146, v160, v148
	v_fmac_f32_e32 v160, v161, v147
	v_fma_f32 v146, -v146, v160, v148
	v_div_fmas_f32 v146, v146, v147, v160
	v_div_fixup_f32 v151, v146, v153, v151
	v_div_scale_f32 v146, s[68:69], v152, v152, v150
	v_rcp_f32_e32 v147, v146
	s_nop 0
	v_fma_f32 v148, -v146, v147, 1.0
	v_fmac_f32_e32 v147, v148, v147
	v_div_scale_f32 v148, vcc, v150, v152, v150
	v_mul_f32_e32 v160, v148, v147
	v_fma_f32 v161, -v146, v160, v148
	v_fmac_f32_e32 v160, v161, v147
	v_fma_f32 v146, -v146, v160, v148
	v_div_fmas_f32 v146, v146, v147, v160
	v_div_fixup_f32 v150, v146, v152, v150
	v_pk_mul_f32 v[154:155], v[150:151], v[150:151]
	v_add_f32_e32 v148, v154, v155
	s_nop 1
	v_add_f32_dpp v148, v148, v148 quad_perm:[1,0,3,2] row_mask:0xf bank_mask:0xf
	s_nop 1
	v_add_f32_dpp v148, v148, v148 quad_perm:[2,3,0,1] row_mask:0xf bank_mask:0xf
	s_nop 1
	v_add_f32_dpp v148, v148, v148 row_half_mirror row_mask:0xf bank_mask:0xf
	s_nop 1
	v_add_f32_dpp v148, v148, v148 row_mirror row_mask:0xf bank_mask:0xf
	v_mov_b32_e32 v154, v148
	s_nop 1
	v_permlane16_swap_b32_e32 v148, v154
	v_add_f32_e32 v148, v148, v154
	v_mov_b32_e32 v154, v148
	s_nop 1
	v_permlane32_swap_b32_e32 v148, v154
	v_add_f32_e32 v148, v148, v154
	v_add_f32_e32 v148, 0x358637bd, v148
	v_cmp_gt_f32_e32 vcc, s3, v148
	v_mul_f32_e32 v154, 0x4b800000, v148
	s_nop 0
	v_cndmask_b32_e32 v148, v148, v154, vcc
	v_rsq_f32_e32 v148, v148
	s_nop 0
	v_mul_f32_e32 v154, 0x45800000, v148
	v_cndmask_b32_e32 v148, v148, v154, vcc
	v_mul_f32_e32 v148, 0x3db504f3, v148
	v_pk_mul_f32 v[150:151], v[150:151], v[148:149] op_sel_hi:[1,0]
	s_nop 0
	v_cvt_pk_bf16_f32 v146, v150, v151
	global_store_dword v[10:11], v146, off offset:256
	s_waitcnt vmcnt(29)
	v_cndmask_b32_e64 v116, 0, v116, s[42:43]
	v_cndmask_b32_e64 v118, 0, v118, s[44:45]
	v_lshlrev_b32_e32 v154, 16, v117
	v_and_b32_e32 v155, 0xffff0000, v117
	v_lshlrev_b32_e32 v156, 16, v116
	v_and_b32_e32 v157, 0xffff0000, v116
	v_lshlrev_b32_e32 v158, 16, v118
	v_and_b32_e32 v159, 0xffff0000, v118
	v_pk_mul_f32 v[150:151], v[50:51], v[154:155]
	s_nop 0
	v_pk_fma_f32 v[150:151], v[48:49], v[156:157], v[150:151]
	v_pk_fma_f32 v[150:151], v[52:53], v[158:159], v[150:151]
	s_nop 0
	v_mul_f32_e32 v146, 0xbfb8aa3b, v150
	v_exp_f32_e32 v152, v146
	v_mul_f32_e32 v146, 0xbfb8aa3b, v151
	v_exp_f32_e32 v153, v146
	s_nop 0
	v_pk_add_f32 v[152:153], v[152:153], 1.0 op_sel_hi:[1,0]
	s_nop 0
	v_div_scale_f32 v146, s[68:69], v153, v153, v151
	v_rcp_f32_e32 v147, v146
	s_nop 0
	v_fma_f32 v148, -v146, v147, 1.0
	v_fmac_f32_e32 v147, v148, v147
	v_div_scale_f32 v148, vcc, v151, v153, v151
	v_mul_f32_e32 v160, v148, v147
	v_fma_f32 v161, -v146, v160, v148
	v_fmac_f32_e32 v160, v161, v147
	v_fma_f32 v146, -v146, v160, v148
	v_div_fmas_f32 v146, v146, v147, v160
	v_div_fixup_f32 v151, v146, v153, v151
	v_div_scale_f32 v146, s[68:69], v152, v152, v150
	v_rcp_f32_e32 v147, v146
	s_nop 0
	v_fma_f32 v148, -v146, v147, 1.0
	v_fmac_f32_e32 v147, v148, v147
	v_div_scale_f32 v148, vcc, v150, v152, v150
	v_mul_f32_e32 v160, v148, v147
	v_fma_f32 v161, -v146, v160, v148
	v_fmac_f32_e32 v160, v161, v147
	v_fma_f32 v146, -v146, v160, v148
	v_div_fmas_f32 v146, v146, v147, v160
	v_div_fixup_f32 v150, v146, v152, v150
	v_pk_mul_f32 v[154:155], v[150:151], v[150:151]
	v_add_f32_e32 v148, v154, v155
	s_nop 1
	v_add_f32_dpp v148, v148, v148 quad_perm:[1,0,3,2] row_mask:0xf bank_mask:0xf
	s_nop 1
	v_add_f32_dpp v148, v148, v148 quad_perm:[2,3,0,1] row_mask:0xf bank_mask:0xf
	s_nop 1
	v_add_f32_dpp v148, v148, v148 row_half_mirror row_mask:0xf bank_mask:0xf
	s_nop 1
	v_add_f32_dpp v148, v148, v148 row_mirror row_mask:0xf bank_mask:0xf
	v_mov_b32_e32 v154, v148
	s_nop 1
	v_permlane16_swap_b32_e32 v148, v154
	v_add_f32_e32 v148, v148, v154
	v_mov_b32_e32 v154, v148
	s_nop 1
	v_permlane32_swap_b32_e32 v148, v154
	v_add_f32_e32 v148, v148, v154
	v_add_f32_e32 v148, 0x358637bd, v148
	v_cmp_gt_f32_e32 vcc, s3, v148
	v_mul_f32_e32 v154, 0x4b800000, v148
	s_nop 0
	v_cndmask_b32_e32 v148, v148, v154, vcc
	v_rsq_f32_e32 v148, v148
	s_nop 0
	v_mul_f32_e32 v154, 0x45800000, v148
	v_cndmask_b32_e32 v148, v148, v154, vcc
	v_mul_f32_e32 v148, 0x3db504f3, v148
	v_pk_mul_f32 v[150:151], v[150:151], v[148:149] op_sel_hi:[1,0]
	s_nop 0
	v_cvt_pk_bf16_f32 v146, v150, v151
	global_store_dword v[10:11], v146, off offset:512
	s_waitcnt vmcnt(27)
	v_cndmask_b32_e64 v119, 0, v119, s[42:43]
	v_cndmask_b32_e64 v121, 0, v121, s[44:45]
	v_lshlrev_b32_e32 v154, 16, v120
	v_and_b32_e32 v155, 0xffff0000, v120
	v_lshlrev_b32_e32 v156, 16, v119
	v_and_b32_e32 v157, 0xffff0000, v119
	v_lshlrev_b32_e32 v158, 16, v121
	v_and_b32_e32 v159, 0xffff0000, v121
	v_pk_mul_f32 v[150:151], v[56:57], v[154:155]
	s_nop 0
	v_pk_fma_f32 v[150:151], v[54:55], v[156:157], v[150:151]
	v_pk_fma_f32 v[150:151], v[58:59], v[158:159], v[150:151]
	s_nop 0
	v_mul_f32_e32 v146, 0xbfb8aa3b, v150
	v_exp_f32_e32 v152, v146
	v_mul_f32_e32 v146, 0xbfb8aa3b, v151
	v_exp_f32_e32 v153, v146
	s_nop 0
	v_pk_add_f32 v[152:153], v[152:153], 1.0 op_sel_hi:[1,0]
	s_nop 0
	v_div_scale_f32 v146, s[68:69], v153, v153, v151
	v_rcp_f32_e32 v147, v146
	s_nop 0
	v_fma_f32 v148, -v146, v147, 1.0
	v_fmac_f32_e32 v147, v148, v147
	v_div_scale_f32 v148, vcc, v151, v153, v151
	v_mul_f32_e32 v160, v148, v147
	v_fma_f32 v161, -v146, v160, v148
	v_fmac_f32_e32 v160, v161, v147
	v_fma_f32 v146, -v146, v160, v148
	v_div_fmas_f32 v146, v146, v147, v160
	v_div_fixup_f32 v151, v146, v153, v151
	v_div_scale_f32 v146, s[68:69], v152, v152, v150
	v_rcp_f32_e32 v147, v146
	s_nop 0
	v_fma_f32 v148, -v146, v147, 1.0
	v_fmac_f32_e32 v147, v148, v147
	v_div_scale_f32 v148, vcc, v150, v152, v150
	v_mul_f32_e32 v160, v148, v147
	v_fma_f32 v161, -v146, v160, v148
	v_fmac_f32_e32 v160, v161, v147
	v_fma_f32 v146, -v146, v160, v148
	v_div_fmas_f32 v146, v146, v147, v160
	v_div_fixup_f32 v150, v146, v152, v150
	v_pk_mul_f32 v[154:155], v[150:151], v[150:151]
	v_add_f32_e32 v148, v154, v155
	s_nop 1
	v_add_f32_dpp v148, v148, v148 quad_perm:[1,0,3,2] row_mask:0xf bank_mask:0xf
	s_nop 1
	v_add_f32_dpp v148, v148, v148 quad_perm:[2,3,0,1] row_mask:0xf bank_mask:0xf
	s_nop 1
	v_add_f32_dpp v148, v148, v148 row_half_mirror row_mask:0xf bank_mask:0xf
	s_nop 1
	v_add_f32_dpp v148, v148, v148 row_mirror row_mask:0xf bank_mask:0xf
	v_mov_b32_e32 v154, v148
	s_nop 1
	v_permlane16_swap_b32_e32 v148, v154
	v_add_f32_e32 v148, v148, v154
	v_mov_b32_e32 v154, v148
	s_nop 1
	v_permlane32_swap_b32_e32 v148, v154
	v_add_f32_e32 v148, v148, v154
	v_add_f32_e32 v148, 0x358637bd, v148
	v_cmp_gt_f32_e32 vcc, s3, v148
	v_mul_f32_e32 v154, 0x4b800000, v148
	s_nop 0
	v_cndmask_b32_e32 v148, v148, v154, vcc
	v_rsq_f32_e32 v148, v148
	s_nop 0
	v_mul_f32_e32 v154, 0x45800000, v148
	v_cndmask_b32_e32 v148, v148, v154, vcc
	v_mul_f32_e32 v148, 0x3db504f3, v148
	v_pk_mul_f32 v[150:151], v[150:151], v[148:149] op_sel_hi:[1,0]
	s_nop 0
	v_cvt_pk_bf16_f32 v146, v150, v151
	global_store_dword v[10:11], v146, off offset:768
	s_waitcnt vmcnt(25)
	v_cndmask_b32_e64 v122, 0, v122, s[42:43]
	v_cndmask_b32_e64 v124, 0, v124, s[44:45]
	v_lshlrev_b32_e32 v154, 16, v123
	v_and_b32_e32 v155, 0xffff0000, v123
	v_lshlrev_b32_e32 v156, 16, v122
	v_and_b32_e32 v157, 0xffff0000, v122
	v_lshlrev_b32_e32 v158, 16, v124
	v_and_b32_e32 v159, 0xffff0000, v124
	v_pk_mul_f32 v[150:151], v[62:63], v[154:155]
	s_nop 0
	v_pk_fma_f32 v[150:151], v[60:61], v[156:157], v[150:151]
	v_pk_fma_f32 v[150:151], v[64:65], v[158:159], v[150:151]
	s_nop 0
	v_mul_f32_e32 v146, 0xbfb8aa3b, v150
	v_exp_f32_e32 v152, v146
	v_mul_f32_e32 v146, 0xbfb8aa3b, v151
	v_exp_f32_e32 v153, v146
	s_nop 0
	v_pk_add_f32 v[152:153], v[152:153], 1.0 op_sel_hi:[1,0]
	s_nop 0
	v_div_scale_f32 v146, s[68:69], v153, v153, v151
	v_rcp_f32_e32 v147, v146
	s_nop 0
	v_fma_f32 v148, -v146, v147, 1.0
	v_fmac_f32_e32 v147, v148, v147
	v_div_scale_f32 v148, vcc, v151, v153, v151
	v_mul_f32_e32 v160, v148, v147
	v_fma_f32 v161, -v146, v160, v148
	v_fmac_f32_e32 v160, v161, v147
	v_fma_f32 v146, -v146, v160, v148
	v_div_fmas_f32 v146, v146, v147, v160
	v_div_fixup_f32 v151, v146, v153, v151
	v_div_scale_f32 v146, s[68:69], v152, v152, v150
	v_rcp_f32_e32 v147, v146
	s_nop 0
	v_fma_f32 v148, -v146, v147, 1.0
	v_fmac_f32_e32 v147, v148, v147
	v_div_scale_f32 v148, vcc, v150, v152, v150
	v_mul_f32_e32 v160, v148, v147
	v_fma_f32 v161, -v146, v160, v148
	v_fmac_f32_e32 v160, v161, v147
	v_fma_f32 v146, -v146, v160, v148
	v_div_fmas_f32 v146, v146, v147, v160
	v_div_fixup_f32 v150, v146, v152, v150
	v_pk_mul_f32 v[154:155], v[150:151], v[150:151]
	v_add_f32_e32 v148, v154, v155
	s_nop 1
	v_add_f32_dpp v148, v148, v148 quad_perm:[1,0,3,2] row_mask:0xf bank_mask:0xf
	s_nop 1
	v_add_f32_dpp v148, v148, v148 quad_perm:[2,3,0,1] row_mask:0xf bank_mask:0xf
	s_nop 1
	v_add_f32_dpp v148, v148, v148 row_half_mirror row_mask:0xf bank_mask:0xf
	s_nop 1
	v_add_f32_dpp v148, v148, v148 row_mirror row_mask:0xf bank_mask:0xf
	v_mov_b32_e32 v154, v148
	s_nop 1
	v_permlane16_swap_b32_e32 v148, v154
	v_add_f32_e32 v148, v148, v154
	v_mov_b32_e32 v154, v148
	s_nop 1
	v_permlane32_swap_b32_e32 v148, v154
	v_add_f32_e32 v148, v148, v154
	v_add_f32_e32 v148, 0x358637bd, v148
	v_cmp_gt_f32_e32 vcc, s3, v148
	v_mul_f32_e32 v154, 0x4b800000, v148
	s_nop 0
	v_cndmask_b32_e32 v148, v148, v154, vcc
	v_rsq_f32_e32 v148, v148
	s_nop 0
	v_mul_f32_e32 v154, 0x45800000, v148
	v_cndmask_b32_e32 v148, v148, v154, vcc
	v_pk_mul_f32 v[150:151], v[150:151], v[148:149] op_sel_hi:[1,0]
	s_nop 0
	v_cvt_pk_bf16_f32 v146, v150, v151
	global_store_dword v[10:11], v146, off offset:1024
	s_waitcnt vmcnt(23)
	v_cndmask_b32_e64 v125, 0, v125, s[42:43]
	v_cndmask_b32_e64 v127, 0, v127, s[44:45]
	v_lshlrev_b32_e32 v154, 16, v126
	v_and_b32_e32 v155, 0xffff0000, v126
	v_lshlrev_b32_e32 v156, 16, v125
	v_and_b32_e32 v157, 0xffff0000, v125
	v_lshlrev_b32_e32 v158, 16, v127
	v_and_b32_e32 v159, 0xffff0000, v127
	v_pk_mul_f32 v[150:151], v[68:69], v[154:155]
	s_nop 0
	v_pk_fma_f32 v[150:151], v[66:67], v[156:157], v[150:151]
	v_pk_fma_f32 v[150:151], v[70:71], v[158:159], v[150:151]
	s_nop 0
	v_mul_f32_e32 v146, 0xbfb8aa3b, v150
	v_exp_f32_e32 v152, v146
	v_mul_f32_e32 v146, 0xbfb8aa3b, v151
	v_exp_f32_e32 v153, v146
	s_nop 0
	v_pk_add_f32 v[152:153], v[152:153], 1.0 op_sel_hi:[1,0]
	s_nop 0
	v_div_scale_f32 v146, s[68:69], v153, v153, v151
	v_rcp_f32_e32 v147, v146
	s_nop 0
	v_fma_f32 v148, -v146, v147, 1.0
	v_fmac_f32_e32 v147, v148, v147
	v_div_scale_f32 v148, vcc, v151, v153, v151
	v_mul_f32_e32 v160, v148, v147
	v_fma_f32 v161, -v146, v160, v148
	v_fmac_f32_e32 v160, v161, v147
	v_fma_f32 v146, -v146, v160, v148
	v_div_fmas_f32 v146, v146, v147, v160
	v_div_fixup_f32 v151, v146, v153, v151
	v_div_scale_f32 v146, s[68:69], v152, v152, v150
	v_rcp_f32_e32 v147, v146
	s_nop 0
	v_fma_f32 v148, -v146, v147, 1.0
	v_fmac_f32_e32 v147, v148, v147
	v_div_scale_f32 v148, vcc, v150, v152, v150
	v_mul_f32_e32 v160, v148, v147
	v_fma_f32 v161, -v146, v160, v148
	v_fmac_f32_e32 v160, v161, v147
	v_fma_f32 v146, -v146, v160, v148
	v_div_fmas_f32 v146, v146, v147, v160
	v_div_fixup_f32 v150, v146, v152, v150
	v_pk_mul_f32 v[154:155], v[150:151], v[150:151]
	v_add_f32_e32 v148, v154, v155
	s_nop 1
	v_add_f32_dpp v148, v148, v148 quad_perm:[1,0,3,2] row_mask:0xf bank_mask:0xf
	s_nop 1
	v_add_f32_dpp v148, v148, v148 quad_perm:[2,3,0,1] row_mask:0xf bank_mask:0xf
	s_nop 1
	v_add_f32_dpp v148, v148, v148 row_half_mirror row_mask:0xf bank_mask:0xf
	s_nop 1
	v_add_f32_dpp v148, v148, v148 row_mirror row_mask:0xf bank_mask:0xf
	v_mov_b32_e32 v154, v148
	s_nop 1
	v_permlane16_swap_b32_e32 v148, v154
	v_add_f32_e32 v148, v148, v154
	v_mov_b32_e32 v154, v148
	s_nop 1
	v_permlane32_swap_b32_e32 v148, v154
	v_add_f32_e32 v148, v148, v154
	v_add_f32_e32 v148, 0x358637bd, v148
	v_cmp_gt_f32_e32 vcc, s3, v148
	v_mul_f32_e32 v154, 0x4b800000, v148
	s_nop 0
	v_cndmask_b32_e32 v148, v148, v154, vcc
	v_rsq_f32_e32 v148, v148
	s_nop 0
	v_mul_f32_e32 v154, 0x45800000, v148
	v_cndmask_b32_e32 v148, v148, v154, vcc
	v_pk_mul_f32 v[150:151], v[150:151], v[148:149] op_sel_hi:[1,0]
	s_nop 0
	v_cvt_pk_bf16_f32 v146, v150, v151
	global_store_dword v[10:11], v146, off offset:1280
	s_waitcnt vmcnt(21)
	v_cndmask_b32_e64 v128, 0, v128, s[42:43]
	v_cndmask_b32_e64 v130, 0, v130, s[44:45]
	v_lshlrev_b32_e32 v154, 16, v129
	v_and_b32_e32 v155, 0xffff0000, v129
	v_lshlrev_b32_e32 v156, 16, v128
	v_and_b32_e32 v157, 0xffff0000, v128
	v_lshlrev_b32_e32 v158, 16, v130
	v_and_b32_e32 v159, 0xffff0000, v130
	v_pk_mul_f32 v[150:151], v[74:75], v[154:155]
	s_nop 0
	v_pk_fma_f32 v[150:151], v[72:73], v[156:157], v[150:151]
	v_pk_fma_f32 v[150:151], v[76:77], v[158:159], v[150:151]
	s_nop 0
	v_mul_f32_e32 v146, 0xbfb8aa3b, v150
	v_exp_f32_e32 v152, v146
	v_mul_f32_e32 v146, 0xbfb8aa3b, v151
	v_exp_f32_e32 v153, v146
	s_nop 0
	v_pk_add_f32 v[152:153], v[152:153], 1.0 op_sel_hi:[1,0]
	s_nop 0
	v_div_scale_f32 v146, s[68:69], v153, v153, v151
	v_rcp_f32_e32 v147, v146
	s_nop 0
	v_fma_f32 v148, -v146, v147, 1.0
	v_fmac_f32_e32 v147, v148, v147
	v_div_scale_f32 v148, vcc, v151, v153, v151
	v_mul_f32_e32 v160, v148, v147
	v_fma_f32 v161, -v146, v160, v148
	v_fmac_f32_e32 v160, v161, v147
	v_fma_f32 v146, -v146, v160, v148
	v_div_fmas_f32 v146, v146, v147, v160
	v_div_fixup_f32 v151, v146, v153, v151
	v_div_scale_f32 v146, s[68:69], v152, v152, v150
	v_rcp_f32_e32 v147, v146
	s_nop 0
	v_fma_f32 v148, -v146, v147, 1.0
	v_fmac_f32_e32 v147, v148, v147
	v_div_scale_f32 v148, vcc, v150, v152, v150
	v_mul_f32_e32 v160, v148, v147
	v_fma_f32 v161, -v146, v160, v148
	v_fmac_f32_e32 v160, v161, v147
	v_fma_f32 v146, -v146, v160, v148
	v_div_fmas_f32 v146, v146, v147, v160
	v_div_fixup_f32 v150, v146, v152, v150
	v_pk_mul_f32 v[154:155], v[150:151], v[150:151]
	v_add_f32_e32 v148, v154, v155
	s_nop 1
	v_add_f32_dpp v148, v148, v148 quad_perm:[1,0,3,2] row_mask:0xf bank_mask:0xf
	s_nop 1
	v_add_f32_dpp v148, v148, v148 quad_perm:[2,3,0,1] row_mask:0xf bank_mask:0xf
	s_nop 1
	v_add_f32_dpp v148, v148, v148 row_half_mirror row_mask:0xf bank_mask:0xf
	s_nop 1
	v_add_f32_dpp v148, v148, v148 row_mirror row_mask:0xf bank_mask:0xf
	v_mov_b32_e32 v154, v148
	s_nop 1
	v_permlane16_swap_b32_e32 v148, v154
	v_add_f32_e32 v148, v148, v154
	v_mov_b32_e32 v154, v148
	s_nop 1
	v_permlane32_swap_b32_e32 v148, v154
	v_add_f32_e32 v148, v148, v154
	v_add_f32_e32 v148, 0x358637bd, v148
	v_cmp_gt_f32_e32 vcc, s3, v148
	v_mul_f32_e32 v154, 0x4b800000, v148
	s_nop 0
	v_cndmask_b32_e32 v148, v148, v154, vcc
	v_rsq_f32_e32 v148, v148
	s_nop 0
	v_mul_f32_e32 v154, 0x45800000, v148
	v_cndmask_b32_e32 v148, v148, v154, vcc
	v_pk_mul_f32 v[150:151], v[150:151], v[148:149] op_sel_hi:[1,0]
	s_nop 0
	v_cvt_pk_bf16_f32 v146, v150, v151
	global_store_dword v[10:11], v146, off offset:1536
	s_waitcnt vmcnt(19)
	v_cndmask_b32_e64 v131, 0, v131, s[42:43]
	v_cndmask_b32_e64 v133, 0, v133, s[44:45]
	v_lshlrev_b32_e32 v154, 16, v132
	v_and_b32_e32 v155, 0xffff0000, v132
	v_lshlrev_b32_e32 v156, 16, v131
	v_and_b32_e32 v157, 0xffff0000, v131
	v_lshlrev_b32_e32 v158, 16, v133
	v_and_b32_e32 v159, 0xffff0000, v133
	v_pk_mul_f32 v[150:151], v[80:81], v[154:155]
	s_nop 0
	v_pk_fma_f32 v[150:151], v[78:79], v[156:157], v[150:151]
	v_pk_fma_f32 v[150:151], v[82:83], v[158:159], v[150:151]
	s_nop 0
	v_mul_f32_e32 v146, 0xbfb8aa3b, v150
	v_exp_f32_e32 v152, v146
	v_mul_f32_e32 v146, 0xbfb8aa3b, v151
	v_exp_f32_e32 v153, v146
	s_nop 0
	v_pk_add_f32 v[152:153], v[152:153], 1.0 op_sel_hi:[1,0]
	s_nop 0
	v_div_scale_f32 v146, s[68:69], v153, v153, v151
	v_rcp_f32_e32 v147, v146
	s_nop 0
	v_fma_f32 v148, -v146, v147, 1.0
	v_fmac_f32_e32 v147, v148, v147
	v_div_scale_f32 v148, vcc, v151, v153, v151
	v_mul_f32_e32 v160, v148, v147
	v_fma_f32 v161, -v146, v160, v148
	v_fmac_f32_e32 v160, v161, v147
	v_fma_f32 v146, -v146, v160, v148
	v_div_fmas_f32 v146, v146, v147, v160
	v_div_fixup_f32 v151, v146, v153, v151
	v_div_scale_f32 v146, s[68:69], v152, v152, v150
	v_rcp_f32_e32 v147, v146
	s_nop 0
	v_fma_f32 v148, -v146, v147, 1.0
	v_fmac_f32_e32 v147, v148, v147
	v_div_scale_f32 v148, vcc, v150, v152, v150
	v_mul_f32_e32 v160, v148, v147
	v_fma_f32 v161, -v146, v160, v148
	v_fmac_f32_e32 v160, v161, v147
	v_fma_f32 v146, -v146, v160, v148
	v_div_fmas_f32 v146, v146, v147, v160
	v_div_fixup_f32 v150, v146, v152, v150
	v_pk_mul_f32 v[154:155], v[150:151], v[150:151]
	v_add_f32_e32 v148, v154, v155
	s_nop 1
	v_add_f32_dpp v148, v148, v148 quad_perm:[1,0,3,2] row_mask:0xf bank_mask:0xf
	s_nop 1
	v_add_f32_dpp v148, v148, v148 quad_perm:[2,3,0,1] row_mask:0xf bank_mask:0xf
	s_nop 1
	v_add_f32_dpp v148, v148, v148 row_half_mirror row_mask:0xf bank_mask:0xf
	s_nop 1
	v_add_f32_dpp v148, v148, v148 row_mirror row_mask:0xf bank_mask:0xf
	v_mov_b32_e32 v154, v148
	s_nop 1
	v_permlane16_swap_b32_e32 v148, v154
	v_add_f32_e32 v148, v148, v154
	v_mov_b32_e32 v154, v148
	s_nop 1
	v_permlane32_swap_b32_e32 v148, v154
	v_add_f32_e32 v148, v148, v154
	v_add_f32_e32 v148, 0x358637bd, v148
	v_cmp_gt_f32_e32 vcc, s3, v148
	v_mul_f32_e32 v154, 0x4b800000, v148
	s_nop 0
	v_cndmask_b32_e32 v148, v148, v154, vcc
	v_rsq_f32_e32 v148, v148
	s_nop 0
	v_mul_f32_e32 v154, 0x45800000, v148
	v_cndmask_b32_e32 v148, v148, v154, vcc
	v_pk_mul_f32 v[150:151], v[150:151], v[148:149] op_sel_hi:[1,0]
	s_nop 0
	v_cvt_pk_bf16_f32 v146, v150, v151
	global_store_dword v[10:11], v146, off offset:1792
	s_waitcnt vmcnt(17)
	v_cndmask_b32_e64 v134, 0, v134, s[42:43]
	v_cndmask_b32_e64 v136, 0, v136, s[44:45]
	v_lshlrev_b32_e32 v154, 16, v135
	v_and_b32_e32 v155, 0xffff0000, v135
	v_lshlrev_b32_e32 v156, 16, v134
	v_and_b32_e32 v157, 0xffff0000, v134
	v_lshlrev_b32_e32 v158, 16, v136
	v_and_b32_e32 v159, 0xffff0000, v136
	v_pk_mul_f32 v[150:151], v[88:89], v[154:155]
	s_nop 0
	v_pk_fma_f32 v[150:151], v[86:87], v[156:157], v[150:151]
	v_pk_fma_f32 v[150:151], v[90:91], v[158:159], v[150:151]
	s_nop 0
	v_mul_f32_e32 v146, 0xbfb8aa3b, v150
	v_exp_f32_e32 v152, v146
	v_mul_f32_e32 v146, 0xbfb8aa3b, v151
	v_exp_f32_e32 v153, v146
	s_nop 0
	v_pk_add_f32 v[152:153], v[152:153], 1.0 op_sel_hi:[1,0]
	s_nop 0
	v_div_scale_f32 v146, s[68:69], v153, v153, v151
	v_rcp_f32_e32 v147, v146
	s_nop 0
	v_fma_f32 v148, -v146, v147, 1.0
	v_fmac_f32_e32 v147, v148, v147
	v_div_scale_f32 v148, vcc, v151, v153, v151
	v_mul_f32_e32 v160, v148, v147
	v_fma_f32 v161, -v146, v160, v148
	v_fmac_f32_e32 v160, v161, v147
	v_fma_f32 v146, -v146, v160, v148
	v_div_fmas_f32 v146, v146, v147, v160
	v_div_fixup_f32 v151, v146, v153, v151
	v_div_scale_f32 v146, s[68:69], v152, v152, v150
	v_rcp_f32_e32 v147, v146
	s_nop 0
	v_fma_f32 v148, -v146, v147, 1.0
	v_fmac_f32_e32 v147, v148, v147
	v_div_scale_f32 v148, vcc, v150, v152, v150
	v_mul_f32_e32 v160, v148, v147
	v_fma_f32 v161, -v146, v160, v148
	v_fmac_f32_e32 v160, v161, v147
	v_fma_f32 v146, -v146, v160, v148
	v_div_fmas_f32 v146, v146, v147, v160
	v_div_fixup_f32 v150, v146, v152, v150
	v_cvt_pk_bf16_f32 v146, v150, v151
	global_store_dword v[10:11], v146, off offset:2048
	s_waitcnt vmcnt(15)
	v_cndmask_b32_e64 v137, 0, v137, s[42:43]
	v_cndmask_b32_e64 v139, 0, v139, s[44:45]
	v_lshlrev_b32_e32 v154, 16, v138
	v_and_b32_e32 v155, 0xffff0000, v138
	v_lshlrev_b32_e32 v156, 16, v137
	v_and_b32_e32 v157, 0xffff0000, v137
	v_lshlrev_b32_e32 v158, 16, v139
	v_and_b32_e32 v159, 0xffff0000, v139
	v_pk_mul_f32 v[150:151], v[94:95], v[154:155]
	s_nop 0
	v_pk_fma_f32 v[150:151], v[92:93], v[156:157], v[150:151]
	v_pk_fma_f32 v[150:151], v[96:97], v[158:159], v[150:151]
	s_nop 0
	v_mul_f32_e32 v146, 0xbfb8aa3b, v150
	v_exp_f32_e32 v152, v146
	v_mul_f32_e32 v146, 0xbfb8aa3b, v151
	v_exp_f32_e32 v153, v146
	s_nop 0
	v_pk_add_f32 v[152:153], v[152:153], 1.0 op_sel_hi:[1,0]
	s_nop 0
	v_div_scale_f32 v146, s[68:69], v153, v153, v151
	v_rcp_f32_e32 v147, v146
	s_nop 0
	v_fma_f32 v148, -v146, v147, 1.0
	v_fmac_f32_e32 v147, v148, v147
	v_div_scale_f32 v148, vcc, v151, v153, v151
	v_mul_f32_e32 v160, v148, v147
	v_fma_f32 v161, -v146, v160, v148
	v_fmac_f32_e32 v160, v161, v147
	v_fma_f32 v146, -v146, v160, v148
	v_div_fmas_f32 v146, v146, v147, v160
	v_div_fixup_f32 v151, v146, v153, v151
	v_div_scale_f32 v146, s[68:69], v152, v152, v150
	v_rcp_f32_e32 v147, v146
	s_nop 0
	v_fma_f32 v148, -v146, v147, 1.0
	v_fmac_f32_e32 v147, v148, v147
	v_div_scale_f32 v148, vcc, v150, v152, v150
	v_mul_f32_e32 v160, v148, v147
	v_fma_f32 v161, -v146, v160, v148
	v_fmac_f32_e32 v160, v161, v147
	v_fma_f32 v146, -v146, v160, v148
	v_div_fmas_f32 v146, v146, v147, v160
	v_div_fixup_f32 v150, v146, v152, v150
	v_cvt_pk_bf16_f32 v146, v150, v151
	global_store_dword v[10:11], v146, off offset:2304
	s_waitcnt vmcnt(13)
	v_cndmask_b32_e64 v140, 0, v140, s[42:43]
	v_cndmask_b32_e64 v142, 0, v142, s[44:45]
	v_lshlrev_b32_e32 v154, 16, v141
	v_and_b32_e32 v155, 0xffff0000, v141
	v_lshlrev_b32_e32 v156, 16, v140
	v_and_b32_e32 v157, 0xffff0000, v140
	v_lshlrev_b32_e32 v158, 16, v142
	v_and_b32_e32 v159, 0xffff0000, v142
	v_pk_mul_f32 v[150:151], v[100:101], v[154:155]
	s_nop 0
	v_pk_fma_f32 v[150:151], v[98:99], v[156:157], v[150:151]
	v_pk_fma_f32 v[150:151], v[102:103], v[158:159], v[150:151]
	s_nop 0
	v_mul_f32_e32 v146, 0xbfb8aa3b, v150
	v_exp_f32_e32 v152, v146
	v_mul_f32_e32 v146, 0xbfb8aa3b, v151
	v_exp_f32_e32 v153, v146
	s_nop 0
	v_pk_add_f32 v[152:153], v[152:153], 1.0 op_sel_hi:[1,0]
	s_nop 0
	v_div_scale_f32 v146, s[68:69], v153, v153, v151
	v_rcp_f32_e32 v147, v146
	s_nop 0
	v_fma_f32 v148, -v146, v147, 1.0
	v_fmac_f32_e32 v147, v148, v147
	v_div_scale_f32 v148, vcc, v151, v153, v151
	v_mul_f32_e32 v160, v148, v147
	v_fma_f32 v161, -v146, v160, v148
	v_fmac_f32_e32 v160, v161, v147
	v_fma_f32 v146, -v146, v160, v148
	v_div_fmas_f32 v146, v146, v147, v160
	v_div_fixup_f32 v151, v146, v153, v151
	v_div_scale_f32 v146, s[68:69], v152, v152, v150
	v_rcp_f32_e32 v147, v146
	s_nop 0
	v_fma_f32 v148, -v146, v147, 1.0
	v_fmac_f32_e32 v147, v148, v147
	v_div_scale_f32 v148, vcc, v150, v152, v150
	v_mul_f32_e32 v160, v148, v147
	v_fma_f32 v161, -v146, v160, v148
	v_fmac_f32_e32 v160, v161, v147
	v_fma_f32 v146, -v146, v160, v148
	v_div_fmas_f32 v146, v146, v147, v160
	v_div_fixup_f32 v150, v146, v152, v150
	v_cvt_pk_bf16_f32 v146, v150, v151
	global_store_dword v[10:11], v146, off offset:2560
	s_waitcnt vmcnt(11)
	v_cndmask_b32_e64 v143, 0, v143, s[42:43]
	v_cndmask_b32_e64 v145, 0, v145, s[44:45]
	v_lshlrev_b32_e32 v154, 16, v144
	v_and_b32_e32 v155, 0xffff0000, v144
	v_lshlrev_b32_e32 v156, 16, v143
	v_and_b32_e32 v157, 0xffff0000, v143
	v_lshlrev_b32_e32 v158, 16, v145
	v_and_b32_e32 v159, 0xffff0000, v145
	v_pk_mul_f32 v[150:151], v[106:107], v[154:155]
	s_nop 0
	v_pk_fma_f32 v[150:151], v[104:105], v[156:157], v[150:151]
	v_pk_fma_f32 v[150:151], v[108:109], v[158:159], v[150:151]
	s_nop 0
	v_mul_f32_e32 v146, 0xbfb8aa3b, v150
	v_exp_f32_e32 v152, v146
	v_mul_f32_e32 v146, 0xbfb8aa3b, v151
	v_exp_f32_e32 v153, v146
	s_nop 0
	v_pk_add_f32 v[152:153], v[152:153], 1.0 op_sel_hi:[1,0]
	s_nop 0
	v_div_scale_f32 v146, s[68:69], v153, v153, v151
	v_rcp_f32_e32 v147, v146
	s_nop 0
	v_fma_f32 v148, -v146, v147, 1.0
	v_fmac_f32_e32 v147, v148, v147
	v_div_scale_f32 v148, vcc, v151, v153, v151
	v_mul_f32_e32 v160, v148, v147
	v_fma_f32 v161, -v146, v160, v148
	v_fmac_f32_e32 v160, v161, v147
	v_fma_f32 v146, -v146, v160, v148
	v_div_fmas_f32 v146, v146, v147, v160
	v_div_fixup_f32 v151, v146, v153, v151
	v_div_scale_f32 v146, s[68:69], v152, v152, v150
	v_rcp_f32_e32 v147, v146
	s_nop 0
	v_fma_f32 v148, -v146, v147, 1.0
	v_fmac_f32_e32 v147, v148, v147
	v_div_scale_f32 v148, vcc, v150, v152, v150
	v_mul_f32_e32 v160, v148, v147
	v_fma_f32 v161, -v146, v160, v148
	v_fmac_f32_e32 v160, v161, v147
	v_fma_f32 v146, -v146, v160, v148
	v_div_fmas_f32 v146, v146, v147, v160
	v_div_fixup_f32 v150, v146, v152, v150
	v_cvt_pk_bf16_f32 v146, v150, v151
	global_store_dword v[10:11], v146, off offset:2816
	s_mov_b64 s[68:69], 0x1800
	v_lshl_add_u64 v[0:1], v[0:1], 0, s[68:69]
	s_mov_b64 s[68:69], 0xc00
	v_lshl_add_u64 v[10:11], v[10:11], 0, s[68:69]
	s_add_i32 s70, s70, 1
	s_cmp_lg_u32 s70, 4
	s_cbranch_scc1 .Lcv_even_tok

.Ldma_m1b_1:
	s_add_i32 s49, s49, 2
	v_mfma_f32_16x16x32_bf16 v[58:61], v[170:173], v[190:193], v[58:61]
	s_cmp_gt_u32 s49, 28
	s_cbranch_scc1 .Ldma_m1b_2
	s_add_u32 m0, s51, s100
	s_addk_i32 m0, 0x4000
	v_lshl_add_u64 v[244:245], v[208:209], 0, v[206:207]
	s_mov_b64 s[98:99], 0x840000
	v_lshl_add_u64 v[246:247], v[244:245], 0, s[98:99]
	global_load_lds_dwordx4 v[246:247], off

.Ldma_m1b_3:
	s_andn2_b64 vcc, exec, s[40:41]
	v_mfma_f32_16x16x32_bf16 v[50:53], v[162:165], v[190:193], v[50:53]
	v_mfma_f32_16x16x32_bf16 v[46:49], v[178:181], v[186:189], v[46:49]
	v_lshl_add_u64 v[208:209], v[208:209], 0, s[26:27]
	v_lshl_add_u64 v[210:211], v[210:211], 0, s[36:37]
	v_lshl_add_u64 v[212:213], v[212:213], 0, s[26:27]
	v_lshl_add_u64 v[214:215], v[214:215], 0, s[36:37]
	v_mfma_f32_16x16x32_bf16 v[42:45], v[170:173], v[186:189], v[42:45]
	v_mfma_f32_16x16x32_bf16 v[38:41], v[166:169], v[186:189], v[38:41]
	v_mfma_f32_16x16x32_bf16 v[34:37], v[162:165], v[186:189], v[34:37]
	v_mfma_f32_16x16x32_bf16 v[30:33], v[178:181], v[182:185], v[30:33]
	v_mfma_f32_16x16x32_bf16 v[18:21], v[170:173], v[182:185], v[18:21]
	v_mfma_f32_16x16x32_bf16 v[12:15], v[166:169], v[182:185], v[12:15]
	v_mfma_f32_16x16x32_bf16 v[4:7], v[162:165], v[182:185], v[4:7]
	v_mfma_f32_16x16x32_bf16 v[0:3], v[178:181], v[174:177], v[0:3]
	v_mfma_f32_16x16x32_bf16 v[26:29], v[170:173], v[174:177], v[26:29]
	v_mfma_f32_16x16x32_bf16 v[22:25], v[166:169], v[174:177], v[22:25]
	v_mfma_f32_16x16x32_bf16 v[8:11], v[162:165], v[174:177], v[8:11]
	s_waitcnt lgkmcnt(0)
	s_cbranch_vccz .LBB0_1141

.Ldma_m1a_3:
	v_mfma_f32_16x16x32_bf16 v[38:41], v[82:85], v[126:129], v[38:41]
	v_mfma_f32_16x16x32_bf16 v[34:37], v[86:89], v[126:129], v[34:37]
	ds_read_b128 v[126:129], v202 offset:1024
	v_mfma_f32_16x16x32_bf16 v[30:33], v[70:73], v[122:125], v[30:33]
	v_mfma_f32_16x16x32_bf16 v[18:21], v[78:81], v[122:125], v[18:21]
	v_mfma_f32_16x16x32_bf16 v[12:15], v[82:85], v[122:125], v[12:15]
	v_mfma_f32_16x16x32_bf16 v[4:7], v[86:89], v[122:125], v[4:7]
	ds_read_b128 v[122:125], v202 offset:2048
	ds_read_b128 v[118:121], v202 offset:3072
	s_nop 0
	ds_read_b128 v[190:193], v202 offset:4096
	ds_read_b128 v[186:189], v202 offset:5120
	ds_read_b128 v[182:185], v202 offset:6144
	v_mfma_f32_16x16x32_bf16 v[0:3], v[70:73], v[174:177], v[0:3]
	v_mfma_f32_16x16x32_bf16 v[26:29], v[78:81], v[174:177], v[26:29]
	v_mfma_f32_16x16x32_bf16 v[22:25], v[82:85], v[174:177], v[22:25]
	v_mfma_f32_16x16x32_bf16 v[8:11], v[86:89], v[174:177], v[8:11]
	ds_read_b128 v[174:177], v202 offset:7168
	s_nop 0
	s_waitcnt lgkmcnt(4)
	v_mfma_f32_16x16x32_bf16 v[158:161], v[178:181], v[130:133], v[158:161]
	v_mfma_f32_16x16x32_bf16 v[154:157], v[170:173], v[130:133], v[154:157]
	v_mfma_f32_16x16x32_bf16 v[150:153], v[166:169], v[130:133], v[150:153]
	v_mfma_f32_16x16x32_bf16 v[146:149], v[162:165], v[130:133], v[146:149]
	v_mfma_f32_16x16x32_bf16 v[142:145], v[178:181], v[126:129], v[142:145]
	v_mfma_f32_16x16x32_bf16 v[138:141], v[170:173], v[126:129], v[138:141]
	v_mfma_f32_16x16x32_bf16 v[134:137], v[166:169], v[126:129], v[134:137]
	v_mfma_f32_16x16x32_bf16 v[114:117], v[162:165], v[126:129], v[114:117]
	v_mfma_f32_16x16x32_bf16 v[110:113], v[178:181], v[122:125], v[110:113]
	v_mfma_f32_16x16x32_bf16 v[106:109], v[170:173], v[122:125], v[106:109]
	v_mfma_f32_16x16x32_bf16 v[102:105], v[166:169], v[122:125], v[102:105]
	v_mfma_f32_16x16x32_bf16 v[98:101], v[162:165], v[122:125], v[98:101]
	v_mfma_f32_16x16x32_bf16 v[94:97], v[178:181], v[118:121], v[94:97]
	v_mfma_f32_16x16x32_bf16 v[90:93], v[170:173], v[118:121], v[90:93]
	v_mfma_f32_16x16x32_bf16 v[74:77], v[166:169], v[118:121], v[74:77]
	v_mfma_f32_16x16x32_bf16 v[66:69], v[162:165], v[118:121], v[66:69]
	s_cbranch_vccnz .LBB0_1170
	s_min_u32 s46, s48, 2
	s_cmp_lg_u32 s46, 2
	s_mov_b64 s[46:47], -1
	s_cbranch_scc0 .LBB0_1168
	s_cmp_lg_u32 s49, 28
	s_cbranch_scc0 .LBB0_1165
	s_waitcnt vmcnt(0)
	s_mov_b64 s[46:47], 0

.LBB0_1170:
	s_cmp_gt_u32 s49, 26
	s_waitcnt lgkmcnt(0)
	s_barrier

.Ldma_m2b_1:
	s_mov_b64 s[44:45], 0x20000
	s_add_i32 s53, s53, 2
	v_mfma_f32_16x16x32_bf16 v[62:65], v[102:105], v[110:113], v[62:65]
	s_cmpk_gt_u32 s53, 0x7a
	s_cbranch_scc1 .Ldma_m2b_2
	s_add_u32 m0, s55, s100
	s_addk_i32 m0, 0x4000
	s_mov_b64 s[98:99], 0x10b0000
	v_lshl_add_u64 v[246:247], v[122:123], 0, s[98:99]
	global_load_lds_dwordx4 v[246:247], off
.Ldma_m2b_2:
	v_lshl_add_u64 v[116:117], v[116:117], 0, s[44:45]
	v_lshl_add_u64 v[118:119], v[118:119], 0, s[36:37]
	s_add_i32 s52, s52, -2
	v_mfma_f32_16x16x32_bf16 v[50:53], v[94:97], v[110:113], v[50:53]
	v_lshl_add_u64 v[120:121], v[120:121], 0, s[36:37]
	s_andn2_b64 vcc, exec, s[40:41]
	v_mfma_f32_16x16x32_bf16 v[42:45], v[90:93], v[110:113], v[42:45]
	v_mfma_f32_16x16x32_bf16 v[26:29], v[106:109], v[98:101], v[26:29]
	v_mfma_f32_16x16x32_bf16 v[30:33], v[102:105], v[98:101], v[30:33]
	v_mfma_f32_16x16x32_bf16 v[78:81], v[94:97], v[98:101], v[78:81]
	v_mfma_f32_16x16x32_bf16 v[58:61], v[90:93], v[98:101], v[58:61]
	s_waitcnt lgkmcnt(0)
	s_cbranch_vccz .LBB0_1242

.Ldma_m2a_2:
	s_nop 0
	ds_read_b128 v[110:113], v133 offset:2048
	v_mfma_f32_16x16x32_bf16 v[26:29], v[0:3], v[98:101], v[26:29]
	v_mfma_f32_16x16x32_bf16 v[30:33], v[4:7], v[98:101], v[30:33]
	v_mfma_f32_16x16x32_bf16 v[78:81], v[8:11], v[98:101], v[78:81]
	v_mfma_f32_16x16x32_bf16 v[58:61], v[12:15], v[98:101], v[58:61]
	ds_read_b128 v[98:101], v133 offset:3072
	s_nop 0
	s_waitcnt lgkmcnt(2)
	v_mfma_f32_16x16x32_bf16 v[86:89], v[106:109], v[22:25], v[86:89]
	v_mfma_f32_16x16x32_bf16 v[82:85], v[102:105], v[22:25], v[82:85]
	v_mfma_f32_16x16x32_bf16 v[74:77], v[94:97], v[22:25], v[74:77]
	v_mfma_f32_16x16x32_bf16 v[66:69], v[90:93], v[22:25], v[66:69]
	v_mfma_f32_16x16x32_bf16 v[54:57], v[106:109], v[18:21], v[54:57]
	v_mfma_f32_16x16x32_bf16 v[46:49], v[102:105], v[18:21], v[46:49]
	v_mfma_f32_16x16x32_bf16 v[38:41], v[94:97], v[18:21], v[38:41]
	v_mfma_f32_16x16x32_bf16 v[34:37], v[90:93], v[18:21], v[34:37]
	s_cbranch_vccnz .LBB0_1276
	s_min_u32 s46, s52, 4
	s_cmp_lg_u32 s46, 4
	s_mov_b64 s[46:47], -1
	s_cbranch_scc0 .LBB0_1274
	s_mov_b64 s[50:51], -1
	s_mov_b64 s[46:47], 0
	s_cmpk_lt_i32 s53, 0x7c
	s_mov_b64 s[48:49], 0
	s_cbranch_scc0 .LBB0_1280
	s_and_b64 vcc, exec, s[50:51]
	s_cbranch_vccnz .LBB0_1283

.LBB0_1276:
	s_cmpk_gt_u32 s53, 0x78
	s_waitcnt lgkmcnt(0)
	s_barrier
